# mode D: next-tile address computation moved into the MFMA-to-VALU hazard gap of the first half (replaces s_nop 9)
# baseline (speedup 1.0000x reference)
; DI f32x16 mfma(bf16x8 a, bf16x8 b, f32x16 c) { return __builtin_amdgcn_mfma_f32_32x32x16_bf16(a, b, c, 0, 0, 0); }
; template <int MODE>
; DI void attn_tile(const Params& p, int layer, int tile, char* smem) {
;     ...
;       f32x16 s0 = negm, s1 = negm;
; #pragma unroll
;       for (int d0 = 0; d0 < NKQ; ++d0) {
;         bf16x8 k0 = *(const bf16x8*)(Kb + d0 * 16);
;         bf16x8 k1 = *(const bf16x8*)(Kb + 32 * KROW + d0 * 16);
;         s0 = mfma(k0, qf[d0], s0);
;         s1 = mfma(k1, qf[d0], s1);
;       }
;       if (MODE == 0) {
;         const float* tb = tbl + (kt * 64 + 4 * h - qpos + 1280);
; #pragma unroll
;         for (int i = 0; i < 16; ++i) { s0[i] += tb[(i & 3) + 8 * (i >> 2)]; s1[i] += tb[32 + (i & 3) + 8 * (i >> 2)]; }
;       }
;       if (MODE == 2) {
;         const float* tb = tbl + (kt - qr + 7) * 31 + (15 - qc);
; #pragma unroll
;         for (int i = 0; i < 16; ++i) {
;           const int kc0 = 4 * h + (i & 3) + 8 * (i >> 2), kc1 = kc0 + 32;
;           const bool v0 = (kc0 >= cs) && (kc0 < cs + 16), v1 = (kc1 >= cs) && (kc1 < cs + 16);
;           const float b0 = tb[v0 ? kc0 : qc], b1 = tb[v1 ? kc1 : qc];
;           s0[i] = v0 ? s0[i] + b0 : NEGBIG;
;           s1[i] = v1 ? s1[i] + b1 : NEGBIG;
;         }
;       }
;       float ma = __builtin_fmaxf(__builtin_fmaxf(s0[0], s0[1]), s0[2]), mb = __builtin_fmaxf(__builtin_fmaxf(s1[0], s1[1]), s1[2]);
; #pragma unroll
;       for (int i = 3; i < 15; i += 2) { ma = __builtin_fmaxf(__builtin_fmaxf(ma, s0[i]), s0[i + 1]); mb = __builtin_fmaxf(__builtin_fmaxf(mb, s1[i]), s1[i + 1]); }
;       float mt = __builtin_fmaxf(__builtin_fmaxf(ma, s0[15]), s1[15]);
;       mt = hmax(__builtin_fmaxf(mt, mb));
.LBB0_116:
	ds_read_b128 v[248:251], v192 offset:6656
	ds_read_b128 v[238:241], v192 offset:6688
	ds_read_b128 v[242:245], v192 offset:6720
	v_add_f32_e32 v50, v50, v66
	v_add_f32_e32 v50, 0, v50
	v_add_f32_e32 v51, v51, v67
	s_waitcnt lgkmcnt(2)
	v_mfma_f32_32x32x16_bf16 v[82:97], v[248:251], v[98:101], v[34:49]
	ds_read_b128 v[248:251], v192 offset:6752
	v_add_f32_e32 v50, v51, v50
	v_add_f32_e32 v51, v52, v68
	v_add_f32_e32 v50, v51, v50
	v_add_f32_e32 v51, v53, v69
	v_add_f32_e32 v50, v51, v50
	v_add_f32_e32 v51, v54, v70
	s_waitcnt lgkmcnt(2)
	v_mfma_f32_32x32x16_bf16 v[82:97], v[238:241], v[102:105], v[82:97]
	ds_read_b128 v[238:241], v192 offset:6784
	v_add_f32_e32 v50, v51, v50
	v_add_f32_e32 v51, v55, v71
	v_add_f32_e32 v50, v51, v50
	v_add_f32_e32 v51, v56, v72
	v_add_f32_e32 v50, v51, v50
	v_add_f32_e32 v51, v162, v73
	s_waitcnt lgkmcnt(2)
	v_mfma_f32_32x32x16_bf16 v[82:97], v[242:245], v[106:109], v[82:97]
	ds_read_b128 v[242:245], v192 offset:6816
	v_add_f32_e32 v50, v51, v50
	v_add_f32_e32 v51, v74, v57
	v_add_f32_e32 v50, v51, v50
	v_add_f32_e32 v51, v75, v58
	v_add_f32_e32 v50, v51, v50
	v_add_f32_e32 v51, v76, v59
	s_waitcnt lgkmcnt(2)
	v_mfma_f32_32x32x16_bf16 v[82:97], v[248:251], v[110:113], v[82:97]
	ds_read_b128 v[248:251], v192
	v_add_f32_e32 v50, v51, v50
	v_add_f32_e32 v51, v77, v60
	v_add_f32_e32 v50, v51, v50
	v_add_f32_e32 v51, v78, v61
	v_add_f32_e32 v50, v51, v50
	v_add_f32_e32 v51, v79, v62
	s_waitcnt lgkmcnt(2)
	v_mfma_f32_32x32x16_bf16 v[82:97], v[238:241], v[126:129], v[82:97]
	ds_read_b128 v[238:241], v192 offset:32
	v_add_f32_e32 v50, v51, v50
	v_add_f32_e32 v51, v80, v63
	v_add_f32_e32 v50, v51, v50
	v_add_f32_e32 v51, v65, v64
	v_add_f32_e32 v50, v51, v50
	s_waitcnt lgkmcnt(2)
	v_mfma_f32_32x32x16_bf16 v[82:97], v[242:245], v[130:133], v[82:97]
	ds_read_b128 v[242:245], v192 offset:64
	v_add_f32_e32 v212, v212, v50
	s_waitcnt lgkmcnt(2)
	v_mfma_f32_32x32x16_bf16 v[66:81], v[248:251], v[98:101], v[34:49]
	ds_read_b128 v[248:251], v192 offset:96
	s_waitcnt lgkmcnt(2)
	v_mfma_f32_32x32x16_bf16 v[66:81], v[238:241], v[102:105], v[66:81]
	ds_read_b128 v[238:241], v192 offset:128
	s_waitcnt lgkmcnt(2)
	v_mfma_f32_32x32x16_bf16 v[66:81], v[242:245], v[106:109], v[66:81]
	ds_read_b128 v[242:245], v192 offset:160
	ds_read_b64_tr_b16 v[174:175], v191 offset:26624
	ds_read_b64_tr_b16 v[176:177], v191 offset:27776
	ds_read_b64_tr_b16 v[172:173], v191 offset:27840
	ds_read_b64_tr_b16 v[170:171], v191 offset:26688
	ds_read_b64_tr_b16 v[166:167], v191 offset:28928
	ds_read_b64_tr_b16 v[168:169], v191 offset:30080
	ds_read_b64_tr_b16 v[164:165], v191 offset:30144
	ds_read_b64_tr_b16 v[162:163], v191 offset:28992
	ds_read_b64_tr_b16 v[158:159], v191 offset:31232
	ds_read_b64_tr_b16 v[160:161], v191 offset:32384
	ds_read_b64_tr_b16 v[156:157], v191 offset:32448
	ds_read_b64_tr_b16 v[154:155], v191 offset:31296
	ds_read_b64_tr_b16 v[146:147], v191 offset:33536
	ds_read_b64_tr_b16 v[148:149], v191 offset:34688
	ds_read_b64_tr_b16 v[152:153], v191 offset:34752
	ds_read_b64_tr_b16 v[150:151], v191 offset:33600
	s_waitcnt lgkmcnt(15)
	v_mfma_f32_32x32x16_bf16 v[66:81], v[248:251], v[110:113], v[66:81]
	v_mfma_f32_32x32x16_bf16 v[66:81], v[238:241], v[126:129], v[66:81]
	v_mfma_f32_32x32x16_bf16 v[66:81], v[242:245], v[130:133], v[66:81]
	s_add_i32 s21, s21, 2
	s_min_u32 s0, s21, 60
	s_lshl_b32 s0, s0, 6
	s_addk_i32 s0, 0xc0
	s_mul_i32 s1, s0, 0x180
	v_add_u32_e32 v0, s1, v182
	v_lshl_add_u64 v[248:249], v[0:1], 1, s[14:15]
	v_add_u32_e32 v0, s1, v184
	v_lshl_add_u64 v[250:251], v[0:1], 1, s[14:15]
	v_lshl_add_u32 v0, s0, 8, v186
	v_lshl_add_u64 v[204:205], v[0:1], 1, s[16:17]
	v_max3_f32 v50, v82, v83, v84
	v_max3_f32 v50, v50, v85, v86
	v_max3_f32 v50, v50, v87, v88
	v_max3_f32 v50, v50, v89, v90
	v_max3_f32 v50, v50, v91, v92
	v_max3_f32 v50, v50, v93, v94
	v_max3_f32 v50, v50, v95, v96
	v_max_f32_e32 v0, v67, v67
	v_max_f32_e32 v208, v66, v66
	v_max_f32_e32 v0, v208, v0
	v_max3_f32 v0, v0, v68, v69
	v_max3_f32 v0, v0, v70, v71
	v_max3_f32 v0, v0, v72, v73
	v_max3_f32 v0, v0, v74, v75
	v_max3_f32 v0, v0, v76, v77
	v_max3_f32 v0, v0, v78, v79
	v_max3_f32 v0, v0, v80, v81
	v_max3_f32 v0, v0, v97, v50
	v_mov_b32_e32 v50, v0
	s_nop 1
	v_permlane32_swap_b32_e32 v0, v50
	v_max_f32_e32 v50, v50, v50
	v_max_f32_e32 v0, v0, v0
	v_max_f32_e32 v0, v0, v50
	v_cmp_lt_f32_e32 vcc, v234, v0
	s_cbranch_vccz .LBB0_118
; DI float fexp2(float x) { return __builtin_amdgcn_exp2f(x); }
; template <int MODE>
; DI void attn_tile(const Params& p, int layer, int tile, char* smem) {
;     ...
;       if (__any(fresh || (started && mt > 8.f))) {
;         float delta = 0.f, al = 1.f;
;         if (fresh) { delta = mt; started = true; }
;         else if (started) { delta = __builtin_fmaxf(mt, 0.f); al = fexp2(-delta); }
;         mref += delta;
;         lsum *= al;
; #pragma unroll
;         for (int i = 0; i < 16; ++i) { o0[i] *= al; o1[i] *= al; s0[i] -= delta; s1[i] -= delta; negm[i] = -mref; }
;       }
	v_and_b32_e32 v50, 1, v211
	v_cmp_eq_u32_e64 s[12:13], 1, v50
	v_cmp_nlt_f32_e64 s[10:11], s33, v0
	s_nop 0
	v_max_f32_e32 v34, v0, v0
	v_max_f32_e32 v34, 0, v34
	v_exp_f32_e64 v35, -v34
	v_cndmask_b32_e64 v0, v0, 0, s[10:11]
	v_cndmask_b32_e64 v0, v0, v34, s[12:13]
	v_add_f32_e32 v210, v210, v0
	s_or_b64 vcc, s[10:11], s[12:13]
	v_cndmask_b32_e64 v34, 1.0, v35, s[12:13]
	v_xor_b32_e32 v50, 0x80000000, v210
	v_cndmask_b32_e32 v211, 1, v211, vcc
	v_and_b32_e32 v235, 1, v211
	v_cmp_eq_u32_e32 vcc, 1, v235
	v_mov_b32_e32 v235, 0x41000000
	v_mov_b32_e32 v236, 0xefa18f08
	v_cndmask_b32_e32 v234, v236, v235, vcc
	v_mul_f32_e32 v212, v212, v34
	v_pk_add_f32 v[66:67], v[66:67], v[0:1] op_sel_hi:[1,0] neg_lo:[0,1] neg_hi:[0,1]
	v_pk_add_f32 v[82:83], v[82:83], v[0:1] op_sel_hi:[1,0] neg_lo:[0,1] neg_hi:[0,1]
	v_pk_add_f32 v[68:69], v[68:69], v[0:1] op_sel_hi:[1,0] neg_lo:[0,1] neg_hi:[0,1]
	v_pk_add_f32 v[84:85], v[84:85], v[0:1] op_sel_hi:[1,0] neg_lo:[0,1] neg_hi:[0,1]
	v_pk_add_f32 v[70:71], v[70:71], v[0:1] op_sel_hi:[1,0] neg_lo:[0,1] neg_hi:[0,1]
	v_pk_add_f32 v[86:87], v[86:87], v[0:1] op_sel_hi:[1,0] neg_lo:[0,1] neg_hi:[0,1]
	v_pk_add_f32 v[72:73], v[72:73], v[0:1] op_sel_hi:[1,0] neg_lo:[0,1] neg_hi:[0,1]
	v_pk_add_f32 v[88:89], v[88:89], v[0:1] op_sel_hi:[1,0] neg_lo:[0,1] neg_hi:[0,1]
	v_pk_add_f32 v[74:75], v[74:75], v[0:1] op_sel_hi:[1,0] neg_lo:[0,1] neg_hi:[0,1]
	v_pk_add_f32 v[90:91], v[90:91], v[0:1] op_sel_hi:[1,0] neg_lo:[0,1] neg_hi:[0,1]
	v_pk_add_f32 v[76:77], v[76:77], v[0:1] op_sel_hi:[1,0] neg_lo:[0,1] neg_hi:[0,1]
	v_pk_add_f32 v[92:93], v[92:93], v[0:1] op_sel_hi:[1,0] neg_lo:[0,1] neg_hi:[0,1]
	v_pk_add_f32 v[78:79], v[78:79], v[0:1] op_sel_hi:[1,0] neg_lo:[0,1] neg_hi:[0,1]
	v_pk_add_f32 v[94:95], v[94:95], v[0:1] op_sel_hi:[1,0] neg_lo:[0,1] neg_hi:[0,1]
	v_pk_mul_f32 v[32:33], v[32:33], v[34:35] op_sel_hi:[1,0]
	v_pk_mul_f32 v[30:31], v[30:31], v[34:35] op_sel_hi:[1,0]
	v_pk_mul_f32 v[28:29], v[28:29], v[34:35] op_sel_hi:[1,0]
	v_pk_mul_f32 v[26:27], v[26:27], v[34:35] op_sel_hi:[1,0]
	v_pk_mul_f32 v[24:25], v[24:25], v[34:35] op_sel_hi:[1,0]
	v_pk_mul_f32 v[22:23], v[22:23], v[34:35] op_sel_hi:[1,0]
	v_pk_mul_f32 v[20:21], v[20:21], v[34:35] op_sel_hi:[1,0]
	v_pk_mul_f32 v[18:19], v[18:19], v[34:35] op_sel_hi:[1,0]
	v_pk_mul_f32 v[16:17], v[16:17], v[34:35] op_sel_hi:[1,0]
	v_pk_mul_f32 v[14:15], v[14:15], v[34:35] op_sel_hi:[1,0]
	v_pk_mul_f32 v[12:13], v[12:13], v[34:35] op_sel_hi:[1,0]
	v_pk_mul_f32 v[10:11], v[10:11], v[34:35] op_sel_hi:[1,0]
	v_pk_mul_f32 v[8:9], v[8:9], v[34:35] op_sel_hi:[1,0]
	v_pk_mul_f32 v[6:7], v[6:7], v[34:35] op_sel_hi:[1,0]
	v_pk_mul_f32 v[4:5], v[4:5], v[34:35] op_sel_hi:[1,0]
	v_pk_mul_f32 v[2:3], v[2:3], v[34:35] op_sel_hi:[1,0]
	v_pk_add_f32 v[80:81], v[80:81], v[0:1] op_sel_hi:[1,0] neg_lo:[0,1] neg_hi:[0,1]
	v_pk_add_f32 v[96:97], v[96:97], v[0:1] op_sel_hi:[1,0] neg_lo:[0,1] neg_hi:[0,1]
	v_mov_b32_e32 v51, v50
	v_mov_b32_e32 v52, v50
	v_mov_b32_e32 v53, v50
	v_mov_b32_e32 v54, v50
	v_mov_b32_e32 v55, v50
	v_mov_b32_e32 v56, v50
	v_mov_b32_e32 v57, v50
	v_mov_b32_e32 v58, v50
	v_mov_b32_e32 v59, v50
	v_mov_b32_e32 v60, v50
	v_mov_b32_e32 v61, v50
	v_mov_b32_e32 v62, v50
	v_mov_b32_e32 v63, v50
	v_mov_b32_e32 v64, v50
	v_mov_b32_e32 v65, v50
	v_mov_b32_e32 v34, v50
	v_mov_b32_e32 v35, v50
	v_mov_b32_e32 v36, v50
	v_mov_b32_e32 v37, v50
	v_mov_b32_e32 v38, v50
	v_mov_b32_e32 v39, v50
	v_mov_b32_e32 v40, v50
	v_mov_b32_e32 v41, v50
	v_mov_b32_e32 v42, v50
	v_mov_b32_e32 v43, v50
	v_mov_b32_e32 v44, v50
	v_mov_b32_e32 v45, v50
	v_mov_b32_e32 v46, v50
	v_mov_b32_e32 v47, v50
	v_mov_b32_e32 v48, v50
	v_mov_b32_e32 v49, v50
	s_branch .LBB0_119

; DI f32x16 mfma(bf16x8 a, bf16x8 b, f32x16 c) { return __builtin_amdgcn_mfma_f32_32x32x16_bf16(a, b, c, 0, 0, 0); }
; template <int MODE>
; DI void attn_tile(const Params& p, int layer, int tile, char* smem) {
;     ...
;       f32x16 s0 = negm, s1 = negm;
; #pragma unroll
;       for (int d0 = 0; d0 < NKQ; ++d0) {
;         bf16x8 k0 = *(const bf16x8*)(Kb + d0 * 16);
;         bf16x8 k1 = *(const bf16x8*)(Kb + 32 * KROW + d0 * 16);
;         s0 = mfma(k0, qf[d0], s0);
;         s1 = mfma(k1, qf[d0], s1);
;       }
;       if (MODE == 0) {
;         const float* tb = tbl + (kt * 64 + 4 * h - qpos + 1280);
; #pragma unroll
;         for (int i = 0; i < 16; ++i) { s0[i] += tb[(i & 3) + 8 * (i >> 2)]; s1[i] += tb[32 + (i & 3) + 8 * (i >> 2)]; }
;       }
;       if (MODE == 2) {
;         const float* tb = tbl + (kt - qr + 7) * 31 + (15 - qc);
; #pragma unroll
;         for (int i = 0; i < 16; ++i) {
;           const int kc0 = 4 * h + (i & 3) + 8 * (i >> 2), kc1 = kc0 + 32;
;           const bool v0 = (kc0 >= cs) && (kc0 < cs + 16), v1 = (kc1 >= cs) && (kc1 < cs + 16);
;           const float b0 = tb[v0 ? kc0 : qc], b1 = tb[v1 ? kc1 : qc];
;           s0[i] = v0 ? s0[i] + b0 : NEGBIG;
;           s1[i] = v1 ? s1[i] + b1 : NEGBIG;
;         }
;       }
;       float ma = __builtin_fmaxf(__builtin_fmaxf(s0[0], s0[1]), s0[2]), mb = __builtin_fmaxf(__builtin_fmaxf(s1[0], s1[1]), s1[2]);
; #pragma unroll
;       for (int i = 3; i < 15; i += 2) { ma = __builtin_fmaxf(__builtin_fmaxf(ma, s0[i]), s0[i + 1]); mb = __builtin_fmaxf(__builtin_fmaxf(mb, s1[i]), s1[i + 1]); }
;       float mt = __builtin_fmaxf(__builtin_fmaxf(ma, s0[15]), s1[15]);
;       mt = hmax(__builtin_fmaxf(mt, mb));
;     ...
;     lstore(rk0, rv0, 1);
;     gload(rk0, rv0, kt0 + j + 3);
;     __syncthreads();
;     if (j + 1 >= ntile) break;
;     compute(1, kt0 + j + 1);
;     lstore(rk1, rv1, 0);
;     gload(rk1, rv1, kt0 + j + 4);
;     __syncthreads();
.LBB0_123:
	s_or_b64 exec, exec, s[0:1]
	s_waitcnt vmcnt(3)
	ds_write_b128 v190, v[114:117] offset:35840
	global_load_dwordx4 v[122:125], v[248:249], off
	global_load_dwordx4 v[118:121], v[250:251], off
	global_load_dwordx4 v[114:117], v[204:205], off
	s_waitcnt lgkmcnt(0)
	s_barrier
	ds_read_b128 v[94:97], v192 offset:13312
	ds_read_b128 v[146:149], v192 offset:13376
	s_waitcnt lgkmcnt(1)
	v_mfma_f32_32x32x16_bf16 v[66:81], v[94:97], v[98:101], v[34:49]
	ds_read_b128 v[94:97], v192 offset:19968
	v_add_f32_e32 v0, v224, v217
	v_add_f32_e32 v0, 0, v0
	v_add_f32_e32 v93, v229, v225
	v_add_f32_e32 v0, v93, v0
	v_add_f32_e32 v93, v218, v215
	v_add_f32_e32 v0, v93, v0
	s_waitcnt lgkmcnt(0)
	v_mfma_f32_32x32x16_bf16 v[50:65], v[94:97], v[98:101], v[34:49]
	ds_read_b128 v[94:97], v192 offset:13344
	v_add_f32_e32 v93, v232, v230
	v_add_f32_e32 v0, v93, v0
	v_add_f32_e32 v93, v214, v213
	v_add_f32_e32 v0, v93, v0
	v_add_f32_e32 v93, v219, v216
	v_add_f32_e32 v0, v93, v0
	s_waitcnt lgkmcnt(0)
	v_mfma_f32_32x32x16_bf16 v[66:81], v[94:97], v[102:105], v[66:81]
	ds_read_b128 v[94:97], v192 offset:20000
	v_add_f32_e32 v93, v233, v231
	v_add_f32_e32 v0, v93, v0
	v_add_f32_e32 v93, v226, v220
	v_add_f32_e32 v0, v93, v0
	v_add_f32_e32 v93, v227, v221
	v_add_f32_e32 v0, v93, v0
	s_waitcnt lgkmcnt(0)
	v_mfma_f32_32x32x16_bf16 v[50:65], v[94:97], v[102:105], v[50:65]
	ds_read_b128 v[94:97], v192 offset:20032
	ds_read_b128 v[150:153], v192 offset:13408
	v_add_f32_e32 v93, v228, v222
	v_add_f32_e32 v0, v93, v0
	v_add_f32_e32 v92, v92, v223
	v_add_f32_e32 v0, v92, v0
	v_add_f32_e32 v88, v90, v88
	v_add_f32_e32 v0, v88, v0
	v_mfma_f32_32x32x16_bf16 v[66:81], v[146:149], v[106:109], v[66:81]
	ds_read_b128 v[146:149], v192 offset:20064
	v_add_f32_e32 v88, v91, v89
	v_add_f32_e32 v0, v88, v0
	ds_read_b128 v[88:91], v192 offset:13440
	v_add_f32_e32 v86, v87, v86
	v_add_f32_e32 v0, v86, v0
	v_add_f32_e32 v82, v84, v82
	s_waitcnt lgkmcnt(3)
	v_mfma_f32_32x32x16_bf16 v[50:65], v[94:97], v[106:109], v[50:65]
	v_add_f32_e32 v0, v82, v0
	v_add_f32_e32 v86, v85, v83
	ds_read_b128 v[82:85], v192 offset:20096
	ds_read_b128 v[162:165], v192 offset:13472
	v_add_f32_e32 v0, v86, v0
	v_add_f32_e32 v0, v212, v0
	s_waitcnt lgkmcnt(4)
	v_mfma_f32_32x32x16_bf16 v[66:81], v[150:153], v[110:113], v[66:81]
	ds_read_b64_tr_b16 v[158:159], v191 offset:35840
	ds_read_b64_tr_b16 v[160:161], v191 offset:36992
	ds_read_b64_tr_b16 v[156:157], v191 offset:37056
	ds_read_b64_tr_b16 v[154:155], v191 offset:35904
	ds_read_b128 v[166:169], v192 offset:20128
	ds_read_b64_tr_b16 v[150:151], v191 offset:38144
	s_waitcnt lgkmcnt(9)
	v_mfma_f32_32x32x16_bf16 v[50:65], v[146:149], v[110:113], v[50:65]
	s_waitcnt lgkmcnt(8)
	v_mfma_f32_32x32x16_bf16 v[66:81], v[88:91], v[126:129], v[66:81]
	ds_read_b64_tr_b16 v[152:153], v191 offset:39296
	ds_read_b64_tr_b16 v[148:149], v191 offset:39360
	ds_read_b64_tr_b16 v[146:147], v191 offset:38208
	ds_read_b64_tr_b16 v[94:95], v191 offset:40448
	ds_read_b64_tr_b16 v[96:97], v191 offset:41600
	ds_read_b64_tr_b16 v[92:93], v191 offset:41664
	ds_read_b64_tr_b16 v[90:91], v191 offset:40512
	s_waitcnt lgkmcnt(14)
	v_mfma_f32_32x32x16_bf16 v[50:65], v[82:85], v[126:129], v[50:65]
	ds_read_b64_tr_b16 v[82:83], v191 offset:42752
	ds_read_b64_tr_b16 v[84:85], v191 offset:43904
	ds_read_b64_tr_b16 v[88:89], v191 offset:43968
	ds_read_b64_tr_b16 v[86:87], v191 offset:42816
	s_waitcnt lgkmcnt(14)
	v_mfma_f32_32x32x16_bf16 v[66:81], v[162:165], v[130:133], v[66:81]
	s_waitcnt lgkmcnt(12)
	v_mfma_f32_32x32x16_bf16 v[50:65], v[166:169], v[130:133], v[50:65]
	s_nop 9
	v_max_f32_e32 v162, v67, v67
	v_max_f32_e32 v163, v66, v66
	v_max_f32_e32 v162, v163, v162
	v_max3_f32 v162, v162, v68, v69
	v_max3_f32 v162, v162, v70, v71
	v_max3_f32 v162, v162, v72, v73
	v_max3_f32 v162, v162, v74, v75
	v_max3_f32 v163, v50, v51, v52
	v_max3_f32 v163, v163, v53, v54
	v_max3_f32 v163, v163, v55, v56
	v_max3_f32 v163, v163, v57, v58
	v_max3_f32 v163, v163, v59, v60
	v_max3_f32 v162, v162, v76, v77
	v_max3_f32 v163, v163, v61, v62
	v_max3_f32 v162, v162, v78, v79
	v_max3_f32 v163, v163, v63, v64
	v_max3_f32 v162, v162, v80, v81
	v_max3_f32 v162, v162, v65, v163
	v_mov_b32_e32 v163, v162
	s_nop 1
	v_permlane32_swap_b32_e32 v162, v163
	v_max_f32_e32 v163, v163, v163
	v_max_f32_e32 v162, v162, v162
	v_max_f32_e32 v162, v162, v163
	v_cmp_lt_f32_e32 vcc, v234, v162
	s_cbranch_vccz .LBB0_125
; DI float fexp2(float x) { return __builtin_amdgcn_exp2f(x); }
; template <int MODE>
; DI void attn_tile(const Params& p, int layer, int tile, char* smem) {
;     ...
;       if (__any(fresh || (started && mt > 8.f))) {
;         float delta = 0.f, al = 1.f;
;         if (fresh) { delta = mt; started = true; }
;         else if (started) { delta = __builtin_fmaxf(mt, 0.f); al = fexp2(-delta); }
;         mref += delta;
;         lsum *= al;
; #pragma unroll
;         for (int i = 0; i < 16; ++i) { o0[i] *= al; o1[i] *= al; s0[i] -= delta; s1[i] -= delta; negm[i] = -mref; }
;       }
	v_and_b32_e32 v163, 1, v211
	v_cmp_eq_u32_e64 s[12:13], 1, v163
	v_cmp_nlt_f32_e64 s[10:11], s33, v162
	s_nop 0
	v_max_f32_e32 v34, v162, v162
	v_max_f32_e32 v34, 0, v34
	v_exp_f32_e64 v35, -v34
	v_cndmask_b32_e64 v36, v162, 0, s[10:11]
	v_cndmask_b32_e64 v36, v36, v34, s[12:13]
	v_add_f32_e32 v210, v210, v36
	s_or_b64 vcc, s[10:11], s[12:13]
	v_cndmask_b32_e64 v38, 1.0, v35, s[12:13]
	v_xor_b32_e32 v34, 0x80000000, v210
	v_cndmask_b32_e32 v211, 1, v211, vcc
	v_and_b32_e32 v235, 1, v211
	v_cmp_eq_u32_e32 vcc, 1, v235
	v_mov_b32_e32 v235, 0x41000000
	v_mov_b32_e32 v236, 0xefa18f08
	v_cndmask_b32_e32 v234, v236, v235, vcc
	v_mul_f32_e32 v0, v0, v38
	v_pk_add_f32 v[66:67], v[66:67], v[36:37] op_sel_hi:[1,0] neg_lo:[0,1] neg_hi:[0,1]
	v_pk_add_f32 v[50:51], v[50:51], v[36:37] op_sel_hi:[1,0] neg_lo:[0,1] neg_hi:[0,1]
	v_pk_add_f32 v[68:69], v[68:69], v[36:37] op_sel_hi:[1,0] neg_lo:[0,1] neg_hi:[0,1]
	v_pk_add_f32 v[52:53], v[52:53], v[36:37] op_sel_hi:[1,0] neg_lo:[0,1] neg_hi:[0,1]
	v_pk_add_f32 v[70:71], v[70:71], v[36:37] op_sel_hi:[1,0] neg_lo:[0,1] neg_hi:[0,1]
	v_pk_add_f32 v[54:55], v[54:55], v[36:37] op_sel_hi:[1,0] neg_lo:[0,1] neg_hi:[0,1]
	v_pk_add_f32 v[72:73], v[72:73], v[36:37] op_sel_hi:[1,0] neg_lo:[0,1] neg_hi:[0,1]
	v_pk_add_f32 v[56:57], v[56:57], v[36:37] op_sel_hi:[1,0] neg_lo:[0,1] neg_hi:[0,1]
	v_pk_add_f32 v[74:75], v[74:75], v[36:37] op_sel_hi:[1,0] neg_lo:[0,1] neg_hi:[0,1]
	v_pk_add_f32 v[58:59], v[58:59], v[36:37] op_sel_hi:[1,0] neg_lo:[0,1] neg_hi:[0,1]
	v_pk_add_f32 v[76:77], v[76:77], v[36:37] op_sel_hi:[1,0] neg_lo:[0,1] neg_hi:[0,1]
	v_pk_add_f32 v[60:61], v[60:61], v[36:37] op_sel_hi:[1,0] neg_lo:[0,1] neg_hi:[0,1]
	v_pk_add_f32 v[78:79], v[78:79], v[36:37] op_sel_hi:[1,0] neg_lo:[0,1] neg_hi:[0,1]
	v_pk_add_f32 v[62:63], v[62:63], v[36:37] op_sel_hi:[1,0] neg_lo:[0,1] neg_hi:[0,1]
	v_pk_mul_f32 v[32:33], v[32:33], v[38:39] op_sel_hi:[1,0]
	v_pk_mul_f32 v[30:31], v[30:31], v[38:39] op_sel_hi:[1,0]
	v_pk_mul_f32 v[28:29], v[28:29], v[38:39] op_sel_hi:[1,0]
	v_pk_mul_f32 v[26:27], v[26:27], v[38:39] op_sel_hi:[1,0]
	v_pk_mul_f32 v[24:25], v[24:25], v[38:39] op_sel_hi:[1,0]
	v_pk_mul_f32 v[22:23], v[22:23], v[38:39] op_sel_hi:[1,0]
	v_pk_mul_f32 v[20:21], v[20:21], v[38:39] op_sel_hi:[1,0]
	v_pk_mul_f32 v[18:19], v[18:19], v[38:39] op_sel_hi:[1,0]
	v_pk_mul_f32 v[16:17], v[16:17], v[38:39] op_sel_hi:[1,0]
	v_pk_mul_f32 v[14:15], v[14:15], v[38:39] op_sel_hi:[1,0]
	v_pk_mul_f32 v[12:13], v[12:13], v[38:39] op_sel_hi:[1,0]
	v_pk_mul_f32 v[10:11], v[10:11], v[38:39] op_sel_hi:[1,0]
	v_pk_mul_f32 v[8:9], v[8:9], v[38:39] op_sel_hi:[1,0]
	v_pk_mul_f32 v[6:7], v[6:7], v[38:39] op_sel_hi:[1,0]
	v_pk_mul_f32 v[4:5], v[4:5], v[38:39] op_sel_hi:[1,0]
	v_pk_mul_f32 v[2:3], v[2:3], v[38:39] op_sel_hi:[1,0]
	v_pk_add_f32 v[80:81], v[80:81], v[36:37] op_sel_hi:[1,0] neg_lo:[0,1] neg_hi:[0,1]
	v_pk_add_f32 v[64:65], v[64:65], v[36:37] op_sel_hi:[1,0] neg_lo:[0,1] neg_hi:[0,1]
	v_mov_b32_e32 v35, v34
	v_mov_b32_e32 v36, v34
	v_mov_b32_e32 v37, v34
	v_mov_b32_e32 v38, v34
	v_mov_b32_e32 v39, v34
	v_mov_b32_e32 v40, v34
	v_mov_b32_e32 v41, v34
	v_mov_b32_e32 v42, v34
	v_mov_b32_e32 v43, v34
	v_mov_b32_e32 v44, v34
	v_mov_b32_e32 v45, v34
	v_mov_b32_e32 v46, v34
	v_mov_b32_e32 v47, v34
	v_mov_b32_e32 v48, v34
	v_mov_b32_e32 v49, v34
